# P8 down-GEMM epilogue hand-rewritten like P5: x1 loads pipelined 5 chunks deep with counted vmcnt (on top of the previous combination)
# speedup vs baseline: 1.0211x; 1.0001x over previous
.LBB0_991:
	s_lshl_b32 s8, s22, 8
	v_add_u32_e32 v180, s8, v165
	v_lshl_or_b32 v160, s58, 8, v169
	v_readlane_b32 s4, v249, 44
	v_readlane_b32 s5, v249, 45
	s_ashr_i32 s0, s22, 3
	s_mul_hi_i32 s1, s0, 0x6000
	s_mulk_i32 s0, 0x6000
	s_add_u32 s0, s64, s0
	s_addc_u32 s1, s65, s1
	v_mov_b32_e32 v161, 0
	v_lshl_add_u32 v158, v180, 10, v160
	v_mov_b32_e32 v159, 0
	v_lshl_add_u64 v[156:157], v[160:161], 2, s[0:1]
	v_lshl_add_u64 v[162:163], v[158:159], 1, s[4:5]
	v_lshlrev_b32_e32 v181, 1, v158
	global_load_dwordx4 v[132:135], v[156:157], off
	global_load_dwordx4 v[128:131], v[156:157], off offset:16
	s_mov_b32 s10, 0x8000
	s_mov_b32 s11, 0
	s_mov_b32 s12, 0x28000
	s_mov_b32 s13, 0
	s_mov_b32 s14, 0x8000
	s_mov_b32 s15, 0x10000
	s_mov_b32 s23, 0x18000
	s_mov_b32 s24, 0x40000
	s_mov_b32 s32, 0x48000
	s_mov_b32 s55, 0x50000
	s_mov_b32 s74, 0x58000
	v_mov_b64_e32 v[192:193], v[162:163]
	global_load_dwordx4 v[200:203], v[192:193], off nt
	v_lshl_add_u64 v[192:193], v[192:193], 0, s[10:11]
	global_load_dwordx4 v[204:207], v[192:193], off nt
	global_load_dwordx4 v[184:187], v[156:157], off offset:512
	global_load_dwordx4 v[188:191], v[156:157], off offset:528
	v_lshl_add_u64 v[192:193], v[192:193], 0, s[10:11]
	global_load_dwordx4 v[208:211], v[192:193], off nt
	v_lshl_add_u64 v[192:193], v[192:193], 0, s[10:11]
	global_load_dwordx4 v[212:215], v[192:193], off nt
	v_lshl_add_u64 v[192:193], v[192:193], 0, s[12:13]
	global_load_dwordx4 v[216:219], v[192:193], off nt
	v_lshl_add_u64 v[192:193], v[192:193], 0, s[10:11]
	global_load_dwordx4 v[220:223], v[192:193], off nt
	s_waitcnt vmcnt(7)
	v_lshlrev_b32_e32 v224, 16, v200
	v_and_b32_e32 v225, 0xffff0000, v200
	v_lshlrev_b32_e32 v226, 16, v201
	v_and_b32_e32 v227, 0xffff0000, v201
	v_lshlrev_b32_e32 v228, 16, v202
	v_and_b32_e32 v229, 0xffff0000, v202
	v_lshlrev_b32_e32 v230, 16, v203
	v_and_b32_e32 v231, 0xffff0000, v203
	v_pk_fma_f32 v[124:125], v[124:125], v[132:133], v[224:225]
	v_pk_fma_f32 v[126:127], v[126:127], v[134:135], v[226:227]
	v_pk_fma_f32 v[120:121], v[120:121], v[128:129], v[228:229]
	v_pk_fma_f32 v[122:123], v[122:123], v[130:131], v[230:231]
	v_cvt_pk_bf16_f32 v200, v124, v125
	v_cvt_pk_bf16_f32 v201, v126, v127
	v_cvt_pk_bf16_f32 v202, v120, v121
	v_cvt_pk_bf16_f32 v203, v122, v123
	buffer_store_dwordx4 v[200:203], v181, s[16:19], 0 offen sc1
	s_nop 0
	v_lshl_add_u64 v[192:193], v[192:193], 0, s[10:11]
	global_load_dwordx4 v[200:203], v[192:193], off nt
	s_waitcnt vmcnt(8)
	v_lshlrev_b32_e32 v224, 16, v204
	v_and_b32_e32 v225, 0xffff0000, v204
	v_lshlrev_b32_e32 v226, 16, v205
	v_and_b32_e32 v227, 0xffff0000, v205
	v_lshlrev_b32_e32 v228, 16, v206
	v_and_b32_e32 v229, 0xffff0000, v206
	v_lshlrev_b32_e32 v230, 16, v207
	v_and_b32_e32 v231, 0xffff0000, v207
	v_pk_fma_f32 v[116:117], v[116:117], v[132:133], v[224:225]
	v_pk_fma_f32 v[118:119], v[118:119], v[134:135], v[226:227]
	v_pk_fma_f32 v[112:113], v[112:113], v[128:129], v[228:229]
	v_pk_fma_f32 v[114:115], v[114:115], v[130:131], v[230:231]
	v_cvt_pk_bf16_f32 v204, v116, v117
	v_cvt_pk_bf16_f32 v205, v118, v119
	v_cvt_pk_bf16_f32 v206, v112, v113
	v_cvt_pk_bf16_f32 v207, v114, v115
	buffer_store_dwordx4 v[204:207], v181, s[16:19], s14 offen sc1
	s_nop 0
	v_lshl_add_u64 v[192:193], v[192:193], 0, s[10:11]
	global_load_dwordx4 v[204:207], v[192:193], off nt
	s_waitcnt vmcnt(7)
	v_lshlrev_b32_e32 v224, 16, v208
	v_and_b32_e32 v225, 0xffff0000, v208
	v_lshlrev_b32_e32 v226, 16, v209
	v_and_b32_e32 v227, 0xffff0000, v209
	v_lshlrev_b32_e32 v228, 16, v210
	v_and_b32_e32 v229, 0xffff0000, v210
	v_lshlrev_b32_e32 v230, 16, v211
	v_and_b32_e32 v231, 0xffff0000, v211
	v_pk_fma_f32 v[108:109], v[108:109], v[132:133], v[224:225]
	v_pk_fma_f32 v[110:111], v[110:111], v[134:135], v[226:227]
	v_pk_fma_f32 v[104:105], v[104:105], v[128:129], v[228:229]
	v_pk_fma_f32 v[106:107], v[106:107], v[130:131], v[230:231]
	v_cvt_pk_bf16_f32 v208, v108, v109
	v_cvt_pk_bf16_f32 v209, v110, v111
	v_cvt_pk_bf16_f32 v210, v104, v105
	v_cvt_pk_bf16_f32 v211, v106, v107
	buffer_store_dwordx4 v[208:211], v181, s[16:19], s15 offen sc1
	s_nop 0
	v_mov_b64_e32 v[192:193], v[162:163]
	global_load_dwordx4 v[208:211], v[192:193], off offset:256 nt
	s_waitcnt vmcnt(8)
	v_lshlrev_b32_e32 v224, 16, v212
	v_and_b32_e32 v225, 0xffff0000, v212
	v_lshlrev_b32_e32 v226, 16, v213
	v_and_b32_e32 v227, 0xffff0000, v213
	v_lshlrev_b32_e32 v228, 16, v214
	v_and_b32_e32 v229, 0xffff0000, v214
	v_lshlrev_b32_e32 v230, 16, v215
	v_and_b32_e32 v231, 0xffff0000, v215
	v_pk_fma_f32 v[100:101], v[100:101], v[132:133], v[224:225]
	v_pk_fma_f32 v[102:103], v[102:103], v[134:135], v[226:227]
	v_pk_fma_f32 v[96:97], v[96:97], v[128:129], v[228:229]
	v_pk_fma_f32 v[98:99], v[98:99], v[130:131], v[230:231]
	v_cvt_pk_bf16_f32 v212, v100, v101
	v_cvt_pk_bf16_f32 v213, v102, v103
	v_cvt_pk_bf16_f32 v214, v96, v97
	v_cvt_pk_bf16_f32 v215, v98, v99
	buffer_store_dwordx4 v[212:215], v181, s[16:19], s23 offen sc1
	s_nop 0
	v_lshl_add_u64 v[192:193], v[192:193], 0, s[10:11]
	global_load_dwordx4 v[212:215], v[192:193], off offset:256 nt
	s_waitcnt vmcnt(9)
	v_lshlrev_b32_e32 v224, 16, v216
	v_and_b32_e32 v225, 0xffff0000, v216
	v_lshlrev_b32_e32 v226, 16, v217
	v_and_b32_e32 v227, 0xffff0000, v217
	v_lshlrev_b32_e32 v228, 16, v218
	v_and_b32_e32 v229, 0xffff0000, v218
	v_lshlrev_b32_e32 v230, 16, v219
	v_and_b32_e32 v231, 0xffff0000, v219
	v_pk_fma_f32 v[92:93], v[92:93], v[132:133], v[224:225]
	v_pk_fma_f32 v[94:95], v[94:95], v[134:135], v[226:227]
	v_pk_fma_f32 v[88:89], v[88:89], v[128:129], v[228:229]
	v_pk_fma_f32 v[90:91], v[90:91], v[130:131], v[230:231]
	v_cvt_pk_bf16_f32 v216, v92, v93
	v_cvt_pk_bf16_f32 v217, v94, v95
	v_cvt_pk_bf16_f32 v218, v88, v89
	v_cvt_pk_bf16_f32 v219, v90, v91
	buffer_store_dwordx4 v[216:219], v181, s[16:19], s24 offen sc1
	s_nop 0
	v_lshl_add_u64 v[192:193], v[192:193], 0, s[10:11]
	global_load_dwordx4 v[216:219], v[192:193], off offset:256 nt
	s_waitcnt vmcnt(10)
	v_lshlrev_b32_e32 v224, 16, v220
	v_and_b32_e32 v225, 0xffff0000, v220
	v_lshlrev_b32_e32 v226, 16, v221
	v_and_b32_e32 v227, 0xffff0000, v221
	v_lshlrev_b32_e32 v228, 16, v222
	v_and_b32_e32 v229, 0xffff0000, v222
	v_lshlrev_b32_e32 v230, 16, v223
	v_and_b32_e32 v231, 0xffff0000, v223
	v_pk_fma_f32 v[84:85], v[84:85], v[132:133], v[224:225]
	v_pk_fma_f32 v[86:87], v[86:87], v[134:135], v[226:227]
	v_pk_fma_f32 v[80:81], v[80:81], v[128:129], v[228:229]
	v_pk_fma_f32 v[82:83], v[82:83], v[130:131], v[230:231]
	v_cvt_pk_bf16_f32 v220, v84, v85
	v_cvt_pk_bf16_f32 v221, v86, v87
	v_cvt_pk_bf16_f32 v222, v80, v81
	v_cvt_pk_bf16_f32 v223, v82, v83
	buffer_store_dwordx4 v[220:223], v181, s[16:19], s32 offen sc1
	s_nop 0
	v_lshl_add_u64 v[192:193], v[192:193], 0, s[10:11]
	global_load_dwordx4 v[220:223], v[192:193], off offset:256 nt
	s_waitcnt vmcnt(10)
	v_lshlrev_b32_e32 v224, 16, v200
	v_and_b32_e32 v225, 0xffff0000, v200
	v_lshlrev_b32_e32 v226, 16, v201
	v_and_b32_e32 v227, 0xffff0000, v201
	v_lshlrev_b32_e32 v228, 16, v202
	v_and_b32_e32 v229, 0xffff0000, v202
	v_lshlrev_b32_e32 v230, 16, v203
	v_and_b32_e32 v231, 0xffff0000, v203
	v_pk_fma_f32 v[76:77], v[76:77], v[132:133], v[224:225]
	v_pk_fma_f32 v[78:79], v[78:79], v[134:135], v[226:227]
	v_pk_fma_f32 v[72:73], v[72:73], v[128:129], v[228:229]
	v_pk_fma_f32 v[74:75], v[74:75], v[130:131], v[230:231]
	v_cvt_pk_bf16_f32 v200, v76, v77
	v_cvt_pk_bf16_f32 v201, v78, v79
	v_cvt_pk_bf16_f32 v202, v72, v73
	v_cvt_pk_bf16_f32 v203, v74, v75
	buffer_store_dwordx4 v[200:203], v181, s[16:19], s55 offen sc1
	s_nop 0
	v_lshl_add_u64 v[192:193], v[192:193], 0, s[12:13]
	global_load_dwordx4 v[200:203], v[192:193], off offset:256 nt
	s_waitcnt vmcnt(10)
	v_lshlrev_b32_e32 v224, 16, v204
	v_and_b32_e32 v225, 0xffff0000, v204
	v_lshlrev_b32_e32 v226, 16, v205
	v_and_b32_e32 v227, 0xffff0000, v205
	v_lshlrev_b32_e32 v228, 16, v206
	v_and_b32_e32 v229, 0xffff0000, v206
	v_lshlrev_b32_e32 v230, 16, v207
	v_and_b32_e32 v231, 0xffff0000, v207
	v_pk_fma_f32 v[68:69], v[68:69], v[132:133], v[224:225]
	v_pk_fma_f32 v[70:71], v[70:71], v[134:135], v[226:227]
	v_pk_fma_f32 v[64:65], v[64:65], v[128:129], v[228:229]
	v_pk_fma_f32 v[66:67], v[66:67], v[130:131], v[230:231]
	v_cvt_pk_bf16_f32 v204, v68, v69
	v_cvt_pk_bf16_f32 v205, v70, v71
	v_cvt_pk_bf16_f32 v206, v64, v65
	v_cvt_pk_bf16_f32 v207, v66, v67
	buffer_store_dwordx4 v[204:207], v181, s[16:19], s74 offen sc1
	s_nop 0
	v_lshl_add_u64 v[192:193], v[192:193], 0, s[10:11]
	global_load_dwordx4 v[204:207], v[192:193], off offset:256 nt
	s_waitcnt vmcnt(10)
	v_lshlrev_b32_e32 v224, 16, v208
	v_and_b32_e32 v225, 0xffff0000, v208
	v_lshlrev_b32_e32 v226, 16, v209
	v_and_b32_e32 v227, 0xffff0000, v209
	v_lshlrev_b32_e32 v228, 16, v210
	v_and_b32_e32 v229, 0xffff0000, v210
	v_lshlrev_b32_e32 v230, 16, v211
	v_and_b32_e32 v231, 0xffff0000, v211
	v_pk_fma_f32 v[60:61], v[60:61], v[184:185], v[224:225]
	v_pk_fma_f32 v[62:63], v[62:63], v[186:187], v[226:227]
	v_pk_fma_f32 v[56:57], v[56:57], v[188:189], v[228:229]
	v_pk_fma_f32 v[58:59], v[58:59], v[190:191], v[230:231]
	v_cvt_pk_bf16_f32 v208, v60, v61
	v_cvt_pk_bf16_f32 v209, v62, v63
	v_cvt_pk_bf16_f32 v210, v56, v57
	v_cvt_pk_bf16_f32 v211, v58, v59
	buffer_store_dwordx4 v[208:211], v181, s[16:19], 0 offen offset:256 sc1
	s_nop 0
	v_lshl_add_u64 v[192:193], v[192:193], 0, s[10:11]
	global_load_dwordx4 v[208:211], v[192:193], off offset:256 nt
	s_waitcnt vmcnt(10)
	v_lshlrev_b32_e32 v224, 16, v212
	v_and_b32_e32 v225, 0xffff0000, v212
	v_lshlrev_b32_e32 v226, 16, v213
	v_and_b32_e32 v227, 0xffff0000, v213
	v_lshlrev_b32_e32 v228, 16, v214
	v_and_b32_e32 v229, 0xffff0000, v214
	v_lshlrev_b32_e32 v230, 16, v215
	v_and_b32_e32 v231, 0xffff0000, v215
	v_pk_fma_f32 v[52:53], v[52:53], v[184:185], v[224:225]
	v_pk_fma_f32 v[54:55], v[54:55], v[186:187], v[226:227]
	v_pk_fma_f32 v[48:49], v[48:49], v[188:189], v[228:229]
	v_pk_fma_f32 v[50:51], v[50:51], v[190:191], v[230:231]
	v_cvt_pk_bf16_f32 v212, v52, v53
	v_cvt_pk_bf16_f32 v213, v54, v55
	v_cvt_pk_bf16_f32 v214, v48, v49
	v_cvt_pk_bf16_f32 v215, v50, v51
	buffer_store_dwordx4 v[212:215], v181, s[16:19], s14 offen offset:256 sc1
	s_nop 0
	v_lshl_add_u64 v[192:193], v[192:193], 0, s[10:11]
	global_load_dwordx4 v[212:215], v[192:193], off offset:256 nt
	s_waitcnt vmcnt(10)
	v_lshlrev_b32_e32 v224, 16, v216
	v_and_b32_e32 v225, 0xffff0000, v216
	v_lshlrev_b32_e32 v226, 16, v217
	v_and_b32_e32 v227, 0xffff0000, v217
	v_lshlrev_b32_e32 v228, 16, v218
	v_and_b32_e32 v229, 0xffff0000, v218
	v_lshlrev_b32_e32 v230, 16, v219
	v_and_b32_e32 v231, 0xffff0000, v219
	v_pk_fma_f32 v[44:45], v[44:45], v[184:185], v[224:225]
	v_pk_fma_f32 v[46:47], v[46:47], v[186:187], v[226:227]
	v_pk_fma_f32 v[40:41], v[40:41], v[188:189], v[228:229]
	v_pk_fma_f32 v[42:43], v[42:43], v[190:191], v[230:231]
	v_cvt_pk_bf16_f32 v216, v44, v45
	v_cvt_pk_bf16_f32 v217, v46, v47
	v_cvt_pk_bf16_f32 v218, v40, v41
	v_cvt_pk_bf16_f32 v219, v42, v43
	buffer_store_dwordx4 v[216:219], v181, s[16:19], s15 offen offset:256 sc1
	s_waitcnt vmcnt(9)
	v_lshlrev_b32_e32 v224, 16, v220
	v_and_b32_e32 v225, 0xffff0000, v220
	v_lshlrev_b32_e32 v226, 16, v221
	v_and_b32_e32 v227, 0xffff0000, v221
	v_lshlrev_b32_e32 v228, 16, v222
	v_and_b32_e32 v229, 0xffff0000, v222
	v_lshlrev_b32_e32 v230, 16, v223
	v_and_b32_e32 v231, 0xffff0000, v223
	v_pk_fma_f32 v[36:37], v[36:37], v[184:185], v[224:225]
	v_pk_fma_f32 v[38:39], v[38:39], v[186:187], v[226:227]
	v_pk_fma_f32 v[32:33], v[32:33], v[188:189], v[228:229]
	v_pk_fma_f32 v[34:35], v[34:35], v[190:191], v[230:231]
	v_cvt_pk_bf16_f32 v220, v36, v37
	v_cvt_pk_bf16_f32 v221, v38, v39
	v_cvt_pk_bf16_f32 v222, v32, v33
	v_cvt_pk_bf16_f32 v223, v34, v35
	buffer_store_dwordx4 v[220:223], v181, s[16:19], s23 offen offset:256 sc1
	s_waitcnt vmcnt(8)
	v_lshlrev_b32_e32 v224, 16, v200
	v_and_b32_e32 v225, 0xffff0000, v200
	v_lshlrev_b32_e32 v226, 16, v201
	v_and_b32_e32 v227, 0xffff0000, v201
	v_lshlrev_b32_e32 v228, 16, v202
	v_and_b32_e32 v229, 0xffff0000, v202
	v_lshlrev_b32_e32 v230, 16, v203
	v_and_b32_e32 v231, 0xffff0000, v203
	v_pk_fma_f32 v[28:29], v[28:29], v[184:185], v[224:225]
	v_pk_fma_f32 v[30:31], v[30:31], v[186:187], v[226:227]
	v_pk_fma_f32 v[24:25], v[24:25], v[188:189], v[228:229]
	v_pk_fma_f32 v[26:27], v[26:27], v[190:191], v[230:231]
	v_cvt_pk_bf16_f32 v200, v28, v29
	v_cvt_pk_bf16_f32 v201, v30, v31
	v_cvt_pk_bf16_f32 v202, v24, v25
	v_cvt_pk_bf16_f32 v203, v26, v27
	buffer_store_dwordx4 v[200:203], v181, s[16:19], s24 offen offset:256 sc1
	s_waitcnt vmcnt(7)
	v_lshlrev_b32_e32 v224, 16, v204
	v_and_b32_e32 v225, 0xffff0000, v204
	v_lshlrev_b32_e32 v226, 16, v205
	v_and_b32_e32 v227, 0xffff0000, v205
	v_lshlrev_b32_e32 v228, 16, v206
	v_and_b32_e32 v229, 0xffff0000, v206
	v_lshlrev_b32_e32 v230, 16, v207
	v_and_b32_e32 v231, 0xffff0000, v207
	v_pk_fma_f32 v[20:21], v[20:21], v[184:185], v[224:225]
	v_pk_fma_f32 v[22:23], v[22:23], v[186:187], v[226:227]
	v_pk_fma_f32 v[16:17], v[16:17], v[188:189], v[228:229]
	v_pk_fma_f32 v[18:19], v[18:19], v[190:191], v[230:231]
	v_cvt_pk_bf16_f32 v204, v20, v21
	v_cvt_pk_bf16_f32 v205, v22, v23
	v_cvt_pk_bf16_f32 v206, v16, v17
	v_cvt_pk_bf16_f32 v207, v18, v19
	buffer_store_dwordx4 v[204:207], v181, s[16:19], s32 offen offset:256 sc1
	s_waitcnt vmcnt(6)
	v_lshlrev_b32_e32 v224, 16, v208
	v_and_b32_e32 v225, 0xffff0000, v208
	v_lshlrev_b32_e32 v226, 16, v209
	v_and_b32_e32 v227, 0xffff0000, v209
	v_lshlrev_b32_e32 v228, 16, v210
	v_and_b32_e32 v229, 0xffff0000, v210
	v_lshlrev_b32_e32 v230, 16, v211
	v_and_b32_e32 v231, 0xffff0000, v211
	v_pk_fma_f32 v[12:13], v[12:13], v[184:185], v[224:225]
	v_pk_fma_f32 v[14:15], v[14:15], v[186:187], v[226:227]
	v_pk_fma_f32 v[8:9], v[8:9], v[188:189], v[228:229]
	v_pk_fma_f32 v[10:11], v[10:11], v[190:191], v[230:231]
	v_cvt_pk_bf16_f32 v208, v12, v13
	v_cvt_pk_bf16_f32 v209, v14, v15
	v_cvt_pk_bf16_f32 v210, v8, v9
	v_cvt_pk_bf16_f32 v211, v10, v11
	buffer_store_dwordx4 v[208:211], v181, s[16:19], s55 offen offset:256 sc1
	s_waitcnt vmcnt(5)
	v_lshlrev_b32_e32 v224, 16, v212
	v_and_b32_e32 v225, 0xffff0000, v212
	v_lshlrev_b32_e32 v226, 16, v213
	v_and_b32_e32 v227, 0xffff0000, v213
	v_lshlrev_b32_e32 v228, 16, v214
	v_and_b32_e32 v229, 0xffff0000, v214
	v_lshlrev_b32_e32 v230, 16, v215
	v_and_b32_e32 v231, 0xffff0000, v215
	v_pk_fma_f32 v[4:5], v[4:5], v[184:185], v[224:225]
	v_pk_fma_f32 v[6:7], v[6:7], v[186:187], v[226:227]
	v_pk_fma_f32 v[0:1], v[0:1], v[188:189], v[228:229]
	v_pk_fma_f32 v[2:3], v[2:3], v[190:191], v[230:231]
	v_cvt_pk_bf16_f32 v212, v4, v5
	v_cvt_pk_bf16_f32 v213, v6, v7
	v_cvt_pk_bf16_f32 v214, v0, v1
	v_cvt_pk_bf16_f32 v215, v2, v3
	buffer_store_dwordx4 v[212:215], v181, s[16:19], s74 offen offset:256 sc1
	s_mov_b64 s[0:1], -1
	s_and_b64 vcc, exec, s[38:39]
	s_cbranch_vccz .LBB0_1002
	s_waitcnt vmcnt(0)
	s_barrier
	s_and_saveexec_b64 s[0:1], s[92:93]
	s_cbranch_execz .LBB0_998
	s_mov_b64 s[6:7], exec
	v_mbcnt_lo_u32_b32 v0, s6, 0
	v_mbcnt_hi_u32_b32 v0, s7, v0
	v_cmp_eq_u32_e32 vcc, 0, v0
	s_and_saveexec_b64 s[4:5], vcc
	s_cbranch_execz .LBB0_995
	s_ashr_i32 s23, s22, 31
	s_lshl_b64 s[10:11], s[22:23], 2
	s_add_u32 s10, s33, s10
	s_addc_u32 s11, s56, s11
	s_bcnt1_i32_b64 s6, s[6:7]
	v_mov_b32_e32 v1, s6
	global_atomic_add v1, v139, v1, s[10:11] sc0
